# further steal rebalance: FFN1 up conversion also moved from steal-bound ph3 tail to ph6 tail (ph3 keeps FFN1 gate + mix_in + adaLN gemv)
# speedup vs baseline: 1.0045x; 1.0018x over previous
; __device__ __forceinline__ void convert_item(const Args& a, int it, LAS float* scr, int lane) {
;     ...
;         if (it < T_FFN) { const int m = it / 2752, r = it % 2752, f = m / 3, kind = m % 3;
;             if (kind < 2) { k0 = (r / 86) * 64; n0 = (r % 86) * 64; src = a.in[kind ? I_WU : I_WG] + (size_t)f * DM * DFF; ldn = DFF; Kd = DM; dst = WGU + (size_t)f * 2 * DFF * DM; drow = (n0 >> 7) * 256 + kind * 128 + (n0 & 127); }
;             else { k0 = (r / 32) * 64; n0 = (r % 32) * 64; src = a.in[I_WDN] + (size_t)f * DFF * DM; ldn = DM; Kd = DFF; dst = WD + (size_t)f * DM * DFF; drow = n0; }
;     ...
;     for (;;) {
;         __syncthreads();
;         if (tid == 0) bc[0] = (int)__hip_atomic_fetch_add(ctr, (unsigned)NSTEAL, __ATOMIC_RELAXED, __HIP_MEMORY_SCOPE_AGENT);
;         __syncthreads();
;         const int base = bc[0];
;         if (base >= n) break;
;         const int j = base + w;
;         if (w < NSTEAL && j < n) convert_item(a, j < n1 ? lo1 + j : (j < n1 + n2 ? lo2 + (j - n1) : lo3 + (j - n1 - n2)), scr, lane);
.LBB0_214:
	s_or_b64 exec, exec, s[8:9]
	v_mov_b32_e32 v1, s23
	s_waitcnt lgkmcnt(0)
	s_barrier
	ds_read_b32 v1, v1
	s_movk_i32 s8, 0x2aff
	s_waitcnt lgkmcnt(0)
	v_cmp_lt_i32_e32 vcc, s8, v1
	v_readfirstlane_b32 s10, v1
	s_mov_b64 s[8:9], -1
	s_cbranch_vccnz .LBB0_209
	s_add_i32 s8, s10, s4
	s_cmpk_lt_i32 s8, 0x2b00
	s_cselect_b64 s[10:11], -1, 0
	s_and_b64 s[10:11], s[6:7], s[10:11]
	s_andn2_b64 vcc, exec, s[10:11]
	s_cbranch_vccnz .LBB0_208
	s_cmpk_lt_i32 s8, 0x1580
	s_movk_i32 s9, 0x2b00
	s_cselect_b32 s9, s9, 0x2b00
	s_add_i32 s9, s9, s8
	s_mul_hi_i32 s8, s9, 0x2fa0be83
	s_lshr_b32 s10, s8, 31
	s_ashr_i32 s8, s8, 9
	s_add_i32 s8, s8, s10
	s_mul_i32 s10, s8, 0xac0
	s_sub_i32 s14, s9, s10
	s_mul_hi_i32 s9, s9, 0xfe03f81
	s_lshr_b32 s10, s9, 31
	s_ashr_i32 s26, s9, 9
	s_mul_hi_i32 s9, s8, 0x55555556
	s_add_i32 s26, s26, s10
	s_lshr_b32 s10, s9, 31
	s_add_i32 s9, s9, s10
	s_mul_i32 s9, s9, 3
	s_sub_i32 s13, s8, s9
	s_cmp_gt_i32 s13, 1
	s_mov_b64 s[8:9], -1
	s_sext_i32_i16 s18, s14
	s_mul_hi_i32 s15, s26, 0x2b00000
	s_mul_i32 s19, s26, 0x2b00000
	s_cbranch_scc0 .LBB0_218
	s_bfe_u32 s8, s18, 0x5001a
	s_add_i32 s8, s14, s8
	s_sext_i32_i16 s9, s8
	s_and_b32 s8, s8, 0xffe0
	s_sub_i32 s8, s14, s8
	s_sext_i32_i16 s8, s8
	v_readlane_b32 s64, v248, 11
	s_lshr_b32 s12, s9, 5
	s_lshl_b32 s25, s8, 6
	v_readlane_b32 s66, v248, 13
	v_readlane_b32 s67, v248, 14
	s_add_u32 s16, s66, s19
	s_addc_u32 s17, s67, s15
	s_mul_hi_i32 s8, s26, 0x1580000
	s_mul_i32 s26, s26, 0x1580000
	v_readlane_b32 s9, v248, 40
	s_add_u32 s10, s9, s26
	v_readlane_b32 s9, v248, 41
	v_readlane_b32 s65, v248, 12
	v_readlane_b32 s68, v248, 15
	v_readlane_b32 s69, v248, 16
	v_readlane_b32 s70, v248, 17
	v_readlane_b32 s71, v248, 18
	v_readlane_b32 s72, v248, 19
	v_readlane_b32 s73, v248, 20
	v_readlane_b32 s74, v248, 21
	v_readlane_b32 s75, v248, 22
	v_readlane_b32 s76, v248, 23
	v_readlane_b32 s77, v248, 24
	v_readlane_b32 s78, v248, 25
	v_readlane_b32 s79, v248, 26
	s_addc_u32 s11, s9, s8
	s_mov_b64 s[8:9], 0

; __device__ __forceinline__ void convert_item(const Args& a, int it, LAS float* scr, int lane) {
;     ...
;         if (it < T_FFN) { const int m = it / 2752, r = it % 2752, f = m / 3, kind = m % 3;
;             if (kind < 2) { k0 = (r / 86) * 64; n0 = (r % 86) * 64; src = a.in[kind ? I_WU : I_WG] + (size_t)f * DM * DFF; ldn = DFF; Kd = DM; dst = WGU + (size_t)f * 2 * DFF * DM; drow = (n0 >> 7) * 256 + kind * 128 + (n0 & 127); }
;             else { k0 = (r / 32) * 64; n0 = (r % 32) * 64; src = a.in[I_WDN] + (size_t)f * DFF * DM; ldn = DM; Kd = DFF; dst = WD + (size_t)f * DM * DFF; drow = n0; }
;     ...
;         __syncthreads();
;         const int base = bc[0];
;         if (base >= n) break;
;         const int j = base + w;
;         if (w < NSTEAL && j < n) convert_item(a, j < n1 ? lo1 + j : (j < n1 + n2 ? lo2 + (j - n1) : lo3 + (j - n1 - n2)), scr, lane);
.LBB0_372:
	s_or_b64 exec, exec, s[10:11]
	v_mov_b32_e32 v1, s23
	s_waitcnt lgkmcnt(0)
	s_barrier
	ds_read_b32 v1, v1
	s_movk_i32 s10, 0x1ac0
	s_waitcnt lgkmcnt(0)
	v_cmp_gt_i32_e32 vcc, s10, v1
	v_readfirstlane_b32 s12, v1
	s_mov_b64 s[10:11], -1
	s_cbranch_vccz .LBB0_367
	s_add_i32 s12, s12, s4
	s_cmpk_lt_i32 s12, 0x1ac0
	s_cselect_b64 s[10:11], -1, 0
	s_and_b64 s[10:11], s[8:9], s[10:11]
	s_andn2_b64 vcc, exec, s[10:11]
	s_cbranch_vccnz .LBB0_366
	s_cmpk_lt_u32 s12, 0x2b00
	s_movk_i32 s10, 0x7640
	s_cselect_b32 s10, s10, 0x7640
	s_cmpk_gt_i32 s12, 0xabf
	s_cselect_b32 s10, s10, 0x2040
	s_add_i32 s12, s12, s10
	s_cmp_gt_i32 s12, 0x80ff
	s_mov_b64 s[10:11], -1
	s_cbranch_scc0 .LBB0_376
	s_add_i32 s10, s12, 0xffff7f00
	v_readlane_b32 s64, v248, 11
	s_lshr_b32 s10, s10, 1
	v_readlane_b32 s74, v248, 21
	v_readlane_b32 s75, v248, 22
	s_and_b32 s14, s10, 0x7fffffc0
	s_lshl_b32 s10, s12, 6
	v_readlane_b32 s68, v248, 15
	v_readlane_b32 s69, v248, 16
	v_readlane_b32 s76, v248, 23
	v_readlane_b32 s77, v248, 24
	v_readlane_b32 s79, v248, 26
	s_movk_i32 s74, 0x8000
	s_and_b32 s26, s10, 0x1fc0
	s_mov_b64 s[10:11], 0
	v_readlane_b32 s65, v248, 12
	v_readlane_b32 s66, v248, 13
	v_readlane_b32 s67, v248, 14
	v_readlane_b32 s70, v248, 17
	v_readlane_b32 s71, v248, 18
	v_readlane_b32 s72, v248, 19
	v_readlane_b32 s73, v248, 20
	v_readlane_b32 s78, v248, 25
	s_mov_b64 s[76:77], 0x800
	s_mov_b32 s75, -1
	s_mov_b32 s79, 0x800000
	s_mov_b64 s[18:19], s[68:69]
